# e28b: e28 + row-sum reads also in 64-byte contiguous form (lane fq reads slots 4fq..4fq+3 and 16+4fq..)
# speedup vs baseline: 1.0098x; 1.0017x over previous
; __device__ __forceinline__ u32x4 pack8h(const f32x4 v0, const f32x4 v1) { u32x4 w; w.x = pk_h16(v0[0], v0[1]); w.y = pk_h16(v0[2], v0[3]); w.z = pk_h16(v1[0], v1[1]); w.w = pk_h16(v1[2], v1[3]); return w; }
;     __device__ __forceinline__ void operator()(AccRef acc, const Unit& u, int wr, int wc, int fr, int fq) const {
;     ...
;                 for (int mm = 0; mm < 2; ++mm) { const int m = mp * 2 + mm; const int row = row0 + ai * HALF + m * 16; const size_t o = (size_t)row * D + col0; float ss = 0.f;
; #pragma unroll
;                     for (int bj = 0; bj < 2; ++bj) { const f32x4 r0 = xv[mm][bj][0] + gv[bj][0] * acc[ai][bj][m][0], r1 = xv[mm][bj][1] + gv[bj][1] * acc[ai][bj][m][1];
;                         *(u32x4*)(xo + o + bj * HALF) = pack8h(r0, r1);
;                         ss += ((r0[0] * r0[0] + r0[1] * r0[1]) + (r0[2] * r0[2] + r0[3] * r0[3])) + ((r1[0] * r1[0] + r1[1] * r1[1]) + (r1[2] * r1[2] + r1[3] * r1[3])); }
;                     ss += __shfl_xor(ss, 16); ss += __shfl_xor(ss, 32);
.LBB0_1154:
	v_lshl_add_u32 v172, s58, 8, v178
	v_lshrrev_b32_e32 v170, 4, v184
	v_and_b32_e32 v171, 0x60, v180
	v_lshl_or_b32 v170, v170, 2, v171
	v_lshl_or_b32 v170, s22, 8, v170
	v_readlane_b32 s80, v254, 2
	v_readlane_b32 s81, v254, 3
	v_lshlrev_b32_e32 v173, 13, v172
	v_lshlrev_b32_e32 v187, 7, v172
	v_lshlrev_b32_e32 v171, 2, v170
	v_lshl_add_u32 v173, v170, 2, v173
	s_lshl_b32 s18, s22, 2
	s_add_u32 s18, s18, s72
	s_lshl_b32 s18, s18, 2
	s_add_u32 s88, s26, s18
	s_addc_u32 s89, s27, 0
	v_xor_b32_e32 v186, 16, v184
	v_xor_b32_e32 v185, 32, v184
	v_lshrrev_b32_e32 v174, 4, v184
	v_lshlrev_b32_e32 v186, 2, v186
	v_lshlrev_b32_e32 v185, 2, v185
	v_lshl_add_u32 v174, v174, 4, v187
	s_mov_b32 s94, 0x3a000000
	s_mov_b32 s95, 0x358637bd
	s_mov_b64 s[82:83], s[48:49]
	s_lshr_b32 s59, s65, 10
	global_load_dwordx4 v[144:147], v171, s[46:47]
	global_load_dwordx4 v[148:151], v171, s[46:47] offset:64
	global_load_dwordx4 v[152:155], v171, s[46:47] offset:512
	global_load_dwordx4 v[156:159], v171, s[46:47] offset:576
	s_add_u32 s84, s80, 0x20000
	s_addc_u32 s85, s81, 0
	global_load_dwordx4 v[188:191], v173, s[84:85] nt
	global_load_dwordx4 v[192:195], v173, s[84:85] offset:64 nt
	global_load_dwordx4 v[196:199], v173, s[84:85] offset:512 nt
	global_load_dwordx4 v[200:203], v173, s[84:85] offset:576 nt
	s_add_u32 s84, s80, 0x40000
	s_addc_u32 s85, s81, 0
	global_load_dwordx4 v[104:107], v173, s[84:85] nt
	global_load_dwordx4 v[108:111], v173, s[84:85] offset:64 nt
	global_load_dwordx4 v[112:115], v173, s[84:85] offset:512 nt
	global_load_dwordx4 v[120:123], v173, s[84:85] offset:576 nt
	v_permlane16_swap_b32_e32 v140, v136
	v_permlane16_swap_b32_e32 v141, v137
	v_permlane16_swap_b32_e32 v142, v138
	v_permlane16_swap_b32_e32 v143, v139
	v_permlane32_swap_b32_e32 v140, v136
	v_permlane32_swap_b32_e32 v141, v137
	v_permlane32_swap_b32_e32 v142, v138
	v_permlane32_swap_b32_e32 v143, v139
	v_permlane16_swap_b32_e32 v132, v128
	v_permlane16_swap_b32_e32 v133, v129
	v_permlane16_swap_b32_e32 v134, v130
	v_permlane16_swap_b32_e32 v135, v131
	v_permlane32_swap_b32_e32 v132, v128
	v_permlane32_swap_b32_e32 v133, v129
	v_permlane32_swap_b32_e32 v134, v130
	v_permlane32_swap_b32_e32 v135, v131
	v_permlane16_swap_b32_e32 v124, v116
	v_permlane16_swap_b32_e32 v125, v117
	v_permlane16_swap_b32_e32 v126, v118
	v_permlane16_swap_b32_e32 v127, v119
	v_permlane32_swap_b32_e32 v124, v116
	v_permlane32_swap_b32_e32 v125, v117
	v_permlane32_swap_b32_e32 v126, v118
	v_permlane32_swap_b32_e32 v127, v119
	v_permlane16_swap_b32_e32 v100, v96
	v_permlane16_swap_b32_e32 v101, v97
	v_permlane16_swap_b32_e32 v102, v98
	v_permlane16_swap_b32_e32 v103, v99
	v_permlane32_swap_b32_e32 v100, v96
	v_permlane32_swap_b32_e32 v101, v97
	v_permlane32_swap_b32_e32 v102, v98
	v_permlane32_swap_b32_e32 v103, v99
	s_waitcnt vmcnt(12)
	v_pk_fma_f32 v[140:141], v[140:141], v[218:219], v[234:235]
	v_pk_fma_f32 v[142:143], v[142:143], v[220:221], v[236:237]
	v_pk_fma_f32 v[136:137], v[136:137], v[222:223], v[238:239]
	v_pk_fma_f32 v[138:139], v[138:139], v[224:225], v[240:241]
	v_pk_fma_f32 v[132:133], v[132:133], v[226:227], v[242:243]
	v_pk_fma_f32 v[134:135], v[134:135], v[228:229], v[244:245]
	v_pk_fma_f32 v[128:129], v[128:129], v[230:231], v[246:247]
	v_pk_fma_f32 v[130:131], v[130:131], v[232:233], v[248:249]
	s_add_u32 s84, s80, 0x60000
	s_addc_u32 s85, s81, 0
	global_load_dwordx4 v[234:237], v173, s[84:85] nt
	global_load_dwordx4 v[238:241], v173, s[84:85] offset:64 nt
	global_load_dwordx4 v[242:245], v173, s[84:85] offset:512 nt
	global_load_dwordx4 v[246:249], v173, s[84:85] offset:576 nt
	v_pk_mul_f32 v[176:177], v[140:141], v[140:141]
	v_pk_fma_f32 v[176:177], v[142:143], v[142:143], v[176:177]
	v_pk_fma_f32 v[176:177], v[136:137], v[136:137], v[176:177]
	v_pk_fma_f32 v[176:177], v[138:139], v[138:139], v[176:177]
	v_pk_fma_f32 v[176:177], v[132:133], v[132:133], v[176:177]
	v_pk_fma_f32 v[176:177], v[134:135], v[134:135], v[176:177]
	v_pk_fma_f32 v[176:177], v[128:129], v[128:129], v[176:177]
	v_pk_fma_f32 v[176:177], v[130:131], v[130:131], v[176:177]
	v_add_f32_e32 v204, v176, v177
	v_permlane16_swap_b32_e32 v92, v88
	v_permlane16_swap_b32_e32 v93, v89
	v_permlane16_swap_b32_e32 v94, v90
	v_permlane16_swap_b32_e32 v95, v91
	v_permlane32_swap_b32_e32 v92, v88
	v_permlane32_swap_b32_e32 v93, v89
	v_permlane32_swap_b32_e32 v94, v90
	v_permlane32_swap_b32_e32 v95, v91
	v_permlane16_swap_b32_e32 v84, v80
	v_permlane16_swap_b32_e32 v85, v81
	v_permlane16_swap_b32_e32 v86, v82
	v_permlane16_swap_b32_e32 v87, v83
	v_permlane32_swap_b32_e32 v84, v80
	v_permlane32_swap_b32_e32 v85, v81
	v_permlane32_swap_b32_e32 v86, v82
	v_permlane32_swap_b32_e32 v87, v83
	s_waitcnt vmcnt(8)
; __device__ __forceinline__ f32x4 ld_nt(const float* p) { return __builtin_nontemporal_load((const f32x4*)p); }
; __device__ __forceinline__ u32x4 pack8h(const f32x4 v0, const f32x4 v1) { u32x4 w; w.x = pk_h16(v0[0], v0[1]); w.y = pk_h16(v0[2], v0[3]); w.z = pk_h16(v1[0], v1[1]); w.w = pk_h16(v1[2], v1[3]); return w; }
;     __device__ __forceinline__ void operator()(AccRef acc, const Unit& u, int wr, int wc, int fr, int fq) const {
;     ...
;                         for (int n = 0; n < 2; ++n) xv[mm][bj][n] = ld_nt(x + (size_t)(row0 + ai * HALF + (mp * 2 + mm) * 16) * D + col0 + bj * HALF + n * 4);
;                 __builtin_amdgcn_sched_barrier(0);
; #pragma unroll
;                 for (int mm = 0; mm < 2; ++mm) { const int m = mp * 2 + mm; const int row = row0 + ai * HALF + m * 16; const size_t o = (size_t)row * D + col0; float ss = 0.f;
; #pragma unroll
;                     for (int bj = 0; bj < 2; ++bj) { const f32x4 r0 = xv[mm][bj][0] + gv[bj][0] * acc[ai][bj][m][0], r1 = xv[mm][bj][1] + gv[bj][1] * acc[ai][bj][m][1];
;                         *(u32x4*)(xo + o + bj * HALF) = pack8h(r0, r1);
;                         ss += ((r0[0] * r0[0] + r0[1] * r0[1]) + (r0[2] * r0[2] + r0[3] * r0[3])) + ((r1[0] * r1[0] + r1[1] * r1[1]) + (r1[2] * r1[2] + r1[3] * r1[3])); }
	v_pk_fma_f32 v[124:125], v[124:125], v[218:219], v[188:189]
	v_pk_fma_f32 v[126:127], v[126:127], v[220:221], v[190:191]
	v_pk_fma_f32 v[116:117], v[116:117], v[222:223], v[192:193]
	v_pk_fma_f32 v[118:119], v[118:119], v[224:225], v[194:195]
	v_pk_fma_f32 v[100:101], v[100:101], v[226:227], v[196:197]
	v_pk_fma_f32 v[102:103], v[102:103], v[228:229], v[198:199]
	v_pk_fma_f32 v[96:97], v[96:97], v[230:231], v[200:201]
	v_pk_fma_f32 v[98:99], v[98:99], v[232:233], v[202:203]
	s_add_u32 s84, s80, 0x100000
	s_addc_u32 s85, s81, 0
	global_load_dwordx4 v[188:191], v173, s[84:85] nt
	global_load_dwordx4 v[192:195], v173, s[84:85] offset:64 nt
	global_load_dwordx4 v[196:199], v173, s[84:85] offset:512 nt
	global_load_dwordx4 v[200:203], v173, s[84:85] offset:576 nt
	v_pk_mul_f32 v[176:177], v[124:125], v[124:125]
	v_pk_fma_f32 v[176:177], v[126:127], v[126:127], v[176:177]
	v_pk_fma_f32 v[176:177], v[116:117], v[116:117], v[176:177]
	v_pk_fma_f32 v[176:177], v[118:119], v[118:119], v[176:177]
	v_pk_fma_f32 v[176:177], v[100:101], v[100:101], v[176:177]
	v_pk_fma_f32 v[176:177], v[102:103], v[102:103], v[176:177]
	v_pk_fma_f32 v[176:177], v[96:97], v[96:97], v[176:177]
	v_pk_fma_f32 v[176:177], v[98:99], v[98:99], v[176:177]
	v_add_f32_e32 v205, v176, v177
	v_permlane16_swap_b32_e32 v76, v72
	v_permlane16_swap_b32_e32 v77, v73
	v_permlane16_swap_b32_e32 v78, v74
	v_permlane16_swap_b32_e32 v79, v75
	v_permlane32_swap_b32_e32 v76, v72
	v_permlane32_swap_b32_e32 v77, v73
	v_permlane32_swap_b32_e32 v78, v74
	v_permlane32_swap_b32_e32 v79, v75
	v_permlane16_swap_b32_e32 v68, v64
	v_permlane16_swap_b32_e32 v69, v65
	v_permlane16_swap_b32_e32 v70, v66
	v_permlane16_swap_b32_e32 v71, v67
	v_permlane32_swap_b32_e32 v68, v64
	v_permlane32_swap_b32_e32 v69, v65
	v_permlane32_swap_b32_e32 v70, v66
	v_permlane32_swap_b32_e32 v71, v67
	s_waitcnt vmcnt(8)
	v_pk_fma_f32 v[92:93], v[92:93], v[218:219], v[104:105]
	v_pk_fma_f32 v[94:95], v[94:95], v[220:221], v[106:107]
	v_pk_fma_f32 v[88:89], v[88:89], v[222:223], v[108:109]
	v_pk_fma_f32 v[90:91], v[90:91], v[224:225], v[110:111]
	v_pk_fma_f32 v[84:85], v[84:85], v[226:227], v[112:113]
	v_pk_fma_f32 v[86:87], v[86:87], v[228:229], v[114:115]
	v_pk_fma_f32 v[80:81], v[80:81], v[230:231], v[120:121]
	v_pk_fma_f32 v[82:83], v[82:83], v[232:233], v[122:123]
	s_add_u32 s84, s80, 0x120000
	s_addc_u32 s85, s81, 0
	global_load_dwordx4 v[104:107], v173, s[84:85] nt
	global_load_dwordx4 v[108:111], v173, s[84:85] offset:64 nt
	global_load_dwordx4 v[112:115], v173, s[84:85] offset:512 nt
	global_load_dwordx4 v[120:123], v173, s[84:85] offset:576 nt
	v_pk_mul_f32 v[176:177], v[92:93], v[92:93]
	v_pk_fma_f32 v[176:177], v[94:95], v[94:95], v[176:177]
	v_pk_fma_f32 v[176:177], v[88:89], v[88:89], v[176:177]
	v_pk_fma_f32 v[176:177], v[90:91], v[90:91], v[176:177]
	v_pk_fma_f32 v[176:177], v[84:85], v[84:85], v[176:177]
	v_pk_fma_f32 v[176:177], v[86:87], v[86:87], v[176:177]
	v_pk_fma_f32 v[176:177], v[80:81], v[80:81], v[176:177]
	v_pk_fma_f32 v[176:177], v[82:83], v[82:83], v[176:177]
	v_add_f32_e32 v206, v176, v177
	v_permlane16_swap_b32_e32 v60, v56
	v_permlane16_swap_b32_e32 v61, v57
	v_permlane16_swap_b32_e32 v62, v58
	v_permlane16_swap_b32_e32 v63, v59
	v_permlane32_swap_b32_e32 v60, v56
	v_permlane32_swap_b32_e32 v61, v57
	v_permlane32_swap_b32_e32 v62, v58
	v_permlane32_swap_b32_e32 v63, v59
	v_permlane16_swap_b32_e32 v52, v48
	v_permlane16_swap_b32_e32 v53, v49
	v_permlane16_swap_b32_e32 v54, v50
	v_permlane16_swap_b32_e32 v55, v51
	v_permlane32_swap_b32_e32 v52, v48
	v_permlane32_swap_b32_e32 v53, v49
	v_permlane32_swap_b32_e32 v54, v50
	v_permlane32_swap_b32_e32 v55, v51
	s_waitcnt vmcnt(8)
	v_pk_fma_f32 v[76:77], v[76:77], v[218:219], v[234:235]
	v_pk_fma_f32 v[78:79], v[78:79], v[220:221], v[236:237]
	v_pk_fma_f32 v[72:73], v[72:73], v[222:223], v[238:239]
	v_pk_fma_f32 v[74:75], v[74:75], v[224:225], v[240:241]
	v_pk_fma_f32 v[68:69], v[68:69], v[226:227], v[242:243]
	v_pk_fma_f32 v[70:71], v[70:71], v[228:229], v[244:245]
	v_pk_fma_f32 v[64:65], v[64:65], v[230:231], v[246:247]
	v_pk_fma_f32 v[66:67], v[66:67], v[232:233], v[248:249]
	s_add_u32 s84, s80, 0x140000
	s_addc_u32 s85, s81, 0
	global_load_dwordx4 v[234:237], v173, s[84:85] nt
	global_load_dwordx4 v[238:241], v173, s[84:85] offset:64 nt
	global_load_dwordx4 v[242:245], v173, s[84:85] offset:512 nt
	global_load_dwordx4 v[246:249], v173, s[84:85] offset:576 nt
	v_pk_mul_f32 v[176:177], v[76:77], v[76:77]
	v_pk_fma_f32 v[176:177], v[78:79], v[78:79], v[176:177]
	v_pk_fma_f32 v[176:177], v[72:73], v[72:73], v[176:177]
	v_pk_fma_f32 v[176:177], v[74:75], v[74:75], v[176:177]
	v_pk_fma_f32 v[176:177], v[68:69], v[68:69], v[176:177]
	v_pk_fma_f32 v[176:177], v[70:71], v[70:71], v[176:177]
	v_pk_fma_f32 v[176:177], v[64:65], v[64:65], v[176:177]
	v_pk_fma_f32 v[176:177], v[66:67], v[66:67], v[176:177]
	v_add_f32_e32 v207, v176, v177
	ds_bpermute_b32 v214, v186, v204
	ds_bpermute_b32 v215, v186, v205
	ds_bpermute_b32 v216, v186, v206
	ds_bpermute_b32 v217, v186, v207
	s_waitcnt lgkmcnt(0)
	v_pk_add_f32 v[204:205], v[204:205], v[214:215]
	v_pk_add_f32 v[206:207], v[206:207], v[216:217]
	ds_bpermute_b32 v214, v185, v204
	ds_bpermute_b32 v215, v185, v205
	ds_bpermute_b32 v216, v185, v206
	ds_bpermute_b32 v217, v185, v207
	s_waitcnt lgkmcnt(0)
; __device__ __forceinline__ u32x4 pack8h(const f32x4 v0, const f32x4 v1) { u32x4 w; w.x = pk_h16(v0[0], v0[1]); w.y = pk_h16(v0[2], v0[3]); w.z = pk_h16(v1[0], v1[1]); w.w = pk_h16(v1[2], v1[3]); return w; }
;     __device__ __forceinline__ void operator()(AccRef acc, const Unit& u, int wr, int wc, int fr, int fq) const {
;     ...
;                 for (int mm = 0; mm < 2; ++mm) { const int m = mp * 2 + mm; const int row = row0 + ai * HALF + m * 16; const size_t o = (size_t)row * D + col0; float ss = 0.f;
; #pragma unroll
;                     for (int bj = 0; bj < 2; ++bj) { const f32x4 r0 = xv[mm][bj][0] + gv[bj][0] * acc[ai][bj][m][0], r1 = xv[mm][bj][1] + gv[bj][1] * acc[ai][bj][m][1];
;                         *(u32x4*)(xo + o + bj * HALF) = pack8h(r0, r1);
;                         ss += ((r0[0] * r0[0] + r0[1] * r0[1]) + (r0[2] * r0[2] + r0[3] * r0[3])) + ((r1[0] * r1[0] + r1[1] * r1[1]) + (r1[2] * r1[2] + r1[3] * r1[3])); }
;                     ss += __shfl_xor(ss, 16); ss += __shfl_xor(ss, 32);
;                     if (fq == 0) rowss[(size_t)row * 32 + u.pn * 4 + wc] = ss; } }
	v_pk_add_f32 v[204:205], v[204:205], v[214:215]
	v_pk_add_f32 v[206:207], v[206:207], v[216:217]
	s_and_saveexec_b64 s[20:21], s[2:3]
	s_mov_b64 s[90:91], s[88:89]
	global_store_dword v187, v204, s[90:91] sc0 sc1
	s_add_u32 s90, s88, 0x800
	s_addc_u32 s91, s89, 0
	global_store_dword v187, v205, s[90:91] sc0 sc1
	s_add_u32 s90, s88, 0x1000
	s_addc_u32 s91, s89, 0
	global_store_dword v187, v206, s[90:91] sc0 sc1
	s_add_u32 s90, s88, 0x1800
	s_addc_u32 s91, s89, 0
	global_store_dword v187, v207, s[90:91] sc0 sc1
	s_or_b64 exec, exec, s[20:21]
	s_waitcnt vmcnt(12)
	v_permlane16_swap_b32_e32 v44, v40
	v_permlane16_swap_b32_e32 v45, v41
	v_permlane16_swap_b32_e32 v46, v42
	v_permlane16_swap_b32_e32 v47, v43
	v_permlane32_swap_b32_e32 v44, v40
	v_permlane32_swap_b32_e32 v45, v41
	v_permlane32_swap_b32_e32 v46, v42
	v_permlane32_swap_b32_e32 v47, v43
	v_permlane16_swap_b32_e32 v36, v32
	v_permlane16_swap_b32_e32 v37, v33
	v_permlane16_swap_b32_e32 v38, v34
	v_permlane16_swap_b32_e32 v39, v35
	v_permlane32_swap_b32_e32 v36, v32
	v_permlane32_swap_b32_e32 v37, v33
	v_permlane32_swap_b32_e32 v38, v34
	v_permlane32_swap_b32_e32 v39, v35
	v_pk_fma_f32 v[60:61], v[60:61], v[218:219], v[188:189]
	v_pk_fma_f32 v[62:63], v[62:63], v[220:221], v[190:191]
	v_pk_fma_f32 v[56:57], v[56:57], v[222:223], v[192:193]
	v_pk_fma_f32 v[58:59], v[58:59], v[224:225], v[194:195]
	v_pk_fma_f32 v[52:53], v[52:53], v[226:227], v[196:197]
	v_pk_fma_f32 v[54:55], v[54:55], v[228:229], v[198:199]
	v_pk_fma_f32 v[48:49], v[48:49], v[230:231], v[200:201]
	v_pk_fma_f32 v[50:51], v[50:51], v[232:233], v[202:203]
	s_add_u32 s84, s80, 0x160000
	s_addc_u32 s85, s81, 0
	global_load_dwordx4 v[188:191], v173, s[84:85] nt
	global_load_dwordx4 v[192:195], v173, s[84:85] offset:64 nt
	global_load_dwordx4 v[196:199], v173, s[84:85] offset:512 nt
	global_load_dwordx4 v[200:203], v173, s[84:85] offset:576 nt
	v_pk_mul_f32 v[176:177], v[60:61], v[60:61]
	v_pk_fma_f32 v[176:177], v[62:63], v[62:63], v[176:177]
	v_pk_fma_f32 v[176:177], v[56:57], v[56:57], v[176:177]
	v_pk_fma_f32 v[176:177], v[58:59], v[58:59], v[176:177]
	v_pk_fma_f32 v[176:177], v[52:53], v[52:53], v[176:177]
	v_pk_fma_f32 v[176:177], v[54:55], v[54:55], v[176:177]
	v_pk_fma_f32 v[176:177], v[48:49], v[48:49], v[176:177]
	v_pk_fma_f32 v[176:177], v[50:51], v[50:51], v[176:177]
	v_add_f32_e32 v208, v176, v177
	s_waitcnt vmcnt(12)
	v_permlane16_swap_b32_e32 v28, v24
	v_permlane16_swap_b32_e32 v29, v25
	v_permlane16_swap_b32_e32 v30, v26
	v_permlane16_swap_b32_e32 v31, v27
	v_permlane32_swap_b32_e32 v28, v24
	v_permlane32_swap_b32_e32 v29, v25
	v_permlane32_swap_b32_e32 v30, v26
	v_permlane32_swap_b32_e32 v31, v27
	v_permlane16_swap_b32_e32 v20, v16
	v_permlane16_swap_b32_e32 v21, v17
	v_permlane16_swap_b32_e32 v22, v18
	v_permlane16_swap_b32_e32 v23, v19
	v_permlane32_swap_b32_e32 v20, v16
	v_permlane32_swap_b32_e32 v21, v17
	v_permlane32_swap_b32_e32 v22, v18
	v_permlane32_swap_b32_e32 v23, v19
	v_pk_fma_f32 v[44:45], v[44:45], v[218:219], v[104:105]
	v_pk_fma_f32 v[46:47], v[46:47], v[220:221], v[106:107]
	v_pk_fma_f32 v[40:41], v[40:41], v[222:223], v[108:109]
	v_pk_fma_f32 v[42:43], v[42:43], v[224:225], v[110:111]
	v_pk_fma_f32 v[36:37], v[36:37], v[226:227], v[112:113]
	v_pk_fma_f32 v[38:39], v[38:39], v[228:229], v[114:115]
	v_pk_fma_f32 v[32:33], v[32:33], v[230:231], v[120:121]
	v_pk_fma_f32 v[34:35], v[34:35], v[232:233], v[122:123]
	v_pk_mul_f32 v[176:177], v[44:45], v[44:45]
	v_pk_fma_f32 v[176:177], v[46:47], v[46:47], v[176:177]
	v_pk_fma_f32 v[176:177], v[40:41], v[40:41], v[176:177]
	v_pk_fma_f32 v[176:177], v[42:43], v[42:43], v[176:177]
	v_pk_fma_f32 v[176:177], v[36:37], v[36:37], v[176:177]
	v_pk_fma_f32 v[176:177], v[38:39], v[38:39], v[176:177]
	v_pk_fma_f32 v[176:177], v[32:33], v[32:33], v[176:177]
	v_pk_fma_f32 v[176:177], v[34:35], v[34:35], v[176:177]
	v_add_f32_e32 v209, v176, v177
	s_waitcnt vmcnt(4)
	v_permlane16_swap_b32_e32 v12, v8
	v_permlane16_swap_b32_e32 v13, v9
	v_permlane16_swap_b32_e32 v14, v10
	v_permlane16_swap_b32_e32 v15, v11
	v_permlane32_swap_b32_e32 v12, v8
	v_permlane32_swap_b32_e32 v13, v9
	v_permlane32_swap_b32_e32 v14, v10
	v_permlane32_swap_b32_e32 v15, v11
	v_permlane16_swap_b32_e32 v4, v0
	v_permlane16_swap_b32_e32 v5, v1
	v_permlane16_swap_b32_e32 v6, v2
	v_permlane16_swap_b32_e32 v7, v3
	v_permlane32_swap_b32_e32 v4, v0
	v_permlane32_swap_b32_e32 v5, v1
	v_permlane32_swap_b32_e32 v6, v2
	v_permlane32_swap_b32_e32 v7, v3
	v_pk_fma_f32 v[28:29], v[28:29], v[218:219], v[234:235]
	v_pk_fma_f32 v[30:31], v[30:31], v[220:221], v[236:237]
	v_pk_fma_f32 v[24:25], v[24:25], v[222:223], v[238:239]
	v_pk_fma_f32 v[26:27], v[26:27], v[224:225], v[240:241]
	v_pk_fma_f32 v[20:21], v[20:21], v[226:227], v[242:243]
	v_pk_fma_f32 v[22:23], v[22:23], v[228:229], v[244:245]
	v_pk_fma_f32 v[16:17], v[16:17], v[230:231], v[246:247]
	v_pk_fma_f32 v[18:19], v[18:19], v[232:233], v[248:249]
	v_pk_mul_f32 v[176:177], v[28:29], v[28:29]
	v_pk_fma_f32 v[176:177], v[30:31], v[30:31], v[176:177]
	v_pk_fma_f32 v[176:177], v[24:25], v[24:25], v[176:177]
	v_pk_fma_f32 v[176:177], v[26:27], v[26:27], v[176:177]
	v_pk_fma_f32 v[176:177], v[20:21], v[20:21], v[176:177]
	v_pk_fma_f32 v[176:177], v[22:23], v[22:23], v[176:177]
	v_pk_fma_f32 v[176:177], v[16:17], v[16:17], v[176:177]
	v_pk_fma_f32 v[176:177], v[18:19], v[18:19], v[176:177]
	v_add_f32_e32 v210, v176, v177
	s_barrier
	s_cmp_lg_u32 s59, 0
	s_cbranch_scc1 .Lepi_a1
	s_lshl_b32 s18, s58, 6
	s_add_u32 s18, s18, 0xc000
	s_mov_b64 exec, 1
	v_mov_b32_e32 v175, s18
	v_mov_b32_e32 v255, 1
	global_atomic_add v175, v255, s[50:51]
	s_mov_b64 exec, -1

;     __device__ __forceinline__ void operator()(AccRef acc, const Unit& u, int wr, int wc, int fr, int fq) const {
;     ...
;                     ss += __shfl_xor(ss, 16); ss += __shfl_xor(ss, 32);
;                     if (fq == 0) rowss[(size_t)row * 32 + u.pn * 4 + wc] = ss; } }
; __device__ __forceinline__ void final_rows(int gw, int lane, const f16* xo, float* out, const float* fg, const float* rowss) {
;     ...
;         for (int rr = 0; rr < 4; ++rr) { part[rr] = lane < 32 ? rowss[(size_t)(r0 + rr) * 32 + lane] : 0.f;
; #pragma unroll
;             for (int j = 0; j < 4; ++j) v[rr][j] = *(const u32x4*)(xo + (size_t)(r0 + rr) * D + 512 * j + 8 * lane); }
;         __builtin_amdgcn_sched_barrier(0);
; #pragma unroll
;         for (int rr = 0; rr < 4; ++rr) { const float rstd = rsqrtf(wave_sum(part[rr]) * (1.f / D) + EPS); float* rp = out + (size_t)(r0 + rr) * D + 8 * lane;
.Lepi_b1:
	ds_bpermute_b32 v214, v186, v208
	ds_bpermute_b32 v215, v186, v209
	ds_bpermute_b32 v216, v186, v210
	ds_bpermute_b32 v217, v186, v211
	s_waitcnt lgkmcnt(0)
	v_pk_add_f32 v[208:209], v[208:209], v[214:215]
	v_pk_add_f32 v[210:211], v[210:211], v[216:217]
	ds_bpermute_b32 v214, v185, v208
	ds_bpermute_b32 v215, v185, v209
	ds_bpermute_b32 v216, v185, v210
	ds_bpermute_b32 v217, v185, v211
	s_waitcnt lgkmcnt(0)
	v_pk_add_f32 v[208:209], v[208:209], v[214:215]
	v_pk_add_f32 v[210:211], v[210:211], v[216:217]
	s_and_saveexec_b64 s[20:21], s[2:3]
	s_add_u32 s90, s88, 0x4000
	s_addc_u32 s91, s89, 0
	global_store_dword v187, v208, s[90:91] sc0 sc1
	s_add_u32 s90, s88, 0x4800
	s_addc_u32 s91, s89, 0
	global_store_dword v187, v209, s[90:91] sc0 sc1
	s_add_u32 s90, s88, 0x5000
	s_addc_u32 s91, s89, 0
	global_store_dword v187, v210, s[90:91] sc0 sc1
	s_add_u32 s90, s88, 0x5800
	s_addc_u32 s91, s89, 0
	global_store_dword v187, v211, s[90:91] sc0 sc1
	s_or_b64 exec, exec, s[20:21]
	s_barrier
	s_mov_b64 s[90:91], s[26:27]
	global_load_dwordx4 v[188:191], v174, s[90:91]
	global_load_dwordx4 v[192:195], v174, s[90:91] offset:64
	s_add_u32 s90, s26, 0x800
	s_addc_u32 s91, s27, 0
	global_load_dwordx4 v[196:199], v174, s[90:91]
	global_load_dwordx4 v[200:203], v174, s[90:91] offset:64
	s_add_u32 s90, s26, 0x1000
	s_addc_u32 s91, s27, 0
	global_load_dwordx4 v[104:107], v174, s[90:91]
	global_load_dwordx4 v[108:111], v174, s[90:91] offset:64
	s_add_u32 s90, s26, 0x1800
	s_addc_u32 s91, s27, 0
	global_load_dwordx4 v[112:115], v174, s[90:91]
	global_load_dwordx4 v[120:123], v174, s[90:91] offset:64
	s_waitcnt vmcnt(8)
	s_barrier
	s_cmp_lg_u32 s59, 0
	s_cbranch_scc1 .Lepi_c1
	s_lshl_b32 s18, s58, 6
	s_add_u32 s18, s18, 0xc020
	s_mov_b64 exec, 1
	v_mov_b32_e32 v175, s18
	v_mov_b32_e32 v255, 1
	global_atomic_add v175, v255, s[50:51]
	s_mov_b64 exec, -1

; __device__ __forceinline__ void unpack8h(const u32x4 w, f32x4& v0, f32x4& v1) { v0 = (f32x4){h16lo(w.x), h16hi(w.x), h16lo(w.y), h16hi(w.y)}; v1 = (f32x4){h16lo(w.z), h16hi(w.z), h16lo(w.w), h16hi(w.w)}; }
; __device__ __forceinline__ void final_rows(int gw, int lane, const f16* xo, float* out, const float* fg, const float* rowss) {
;     ...
;         for (int rr = 0; rr < 4; ++rr) { part[rr] = lane < 32 ? rowss[(size_t)(r0 + rr) * 32 + lane] : 0.f;
; #pragma unroll
;             for (int j = 0; j < 4; ++j) v[rr][j] = *(const u32x4*)(xo + (size_t)(r0 + rr) * D + 512 * j + 8 * lane); }
;         __builtin_amdgcn_sched_barrier(0);
; #pragma unroll
;         for (int rr = 0; rr < 4; ++rr) { const float rstd = rsqrtf(wave_sum(part[rr]) * (1.f / D) + EPS); float* rp = out + (size_t)(r0 + rr) * D + 8 * lane;
; #pragma unroll
;             for (int j = 0; j < 4; ++j) { f32x4 a0, a1; unpack8h(v[rr][j], a0, a1); *(f32x4*)(rp + 512 * j) = a0 * rstd * g4[j][0]; *(f32x4*)(rp + 512 * j + 4) = a1 * rstd * g4[j][1]; } }
.Lepi_d2:
	s_barrier
	s_add_u32 s90, s26, 0x4000
	s_addc_u32 s91, s27, 0
	global_load_dwordx4 v[188:191], v174, s[90:91]
	global_load_dwordx4 v[192:195], v174, s[90:91] offset:64
	s_add_u32 s90, s26, 0x4800
	s_addc_u32 s91, s27, 0
	global_load_dwordx4 v[196:199], v174, s[90:91]
	global_load_dwordx4 v[200:203], v174, s[90:91] offset:64
	s_add_u32 s90, s26, 0x5000
	s_addc_u32 s91, s27, 0
	global_load_dwordx4 v[104:107], v174, s[90:91]
	global_load_dwordx4 v[108:111], v174, s[90:91] offset:64
	s_add_u32 s90, s26, 0x5800
	s_addc_u32 s91, s27, 0
	global_load_dwordx4 v[112:115], v174, s[90:91]
	global_load_dwordx4 v[120:123], v174, s[90:91] offset:64
	s_cmp_lg_u32 s59, 0
	s_cbranch_scc1 .Lepi_e1
	s_mov_b64 s[86:87], s[82:83]
	v_pk_mul_f32 v[140:141], v[140:141], v[204:205] op_sel_hi:[1,0]
	v_pk_mul_f32 v[142:143], v[142:143], v[204:205] op_sel_hi:[1,0]
	v_pk_mul_f32 v[140:141], v[140:141], v[144:145]
	v_pk_mul_f32 v[142:143], v[142:143], v[146:147]
	v_pk_mul_f32 v[136:137], v[136:137], v[204:205] op_sel_hi:[1,0]
	v_pk_mul_f32 v[138:139], v[138:139], v[204:205] op_sel_hi:[1,0]
	v_pk_mul_f32 v[136:137], v[136:137], v[148:149]
	v_pk_mul_f32 v[138:139], v[138:139], v[150:151]
	v_pk_mul_f32 v[132:133], v[132:133], v[204:205] op_sel_hi:[1,0]
	v_pk_mul_f32 v[134:135], v[134:135], v[204:205] op_sel_hi:[1,0]
	v_pk_mul_f32 v[132:133], v[132:133], v[152:153]
	v_pk_mul_f32 v[134:135], v[134:135], v[154:155]
	v_pk_mul_f32 v[128:129], v[128:129], v[204:205] op_sel_hi:[1,0]
	v_pk_mul_f32 v[130:131], v[130:131], v[204:205] op_sel_hi:[1,0]
	v_pk_mul_f32 v[128:129], v[128:129], v[156:157]
	v_pk_mul_f32 v[130:131], v[130:131], v[158:159]
	global_store_dwordx4 v173, v[140:143], s[86:87]
	global_store_dwordx4 v173, v[136:139], s[86:87] offset:64
	global_store_dwordx4 v173, v[132:135], s[86:87] offset:512
	global_store_dwordx4 v173, v[128:131], s[86:87] offset:576
	s_add_u32 s86, s82, 0x20000
	s_addc_u32 s87, s83, 0
	v_pk_mul_f32 v[124:125], v[124:125], v[206:207] op_sel_hi:[1,0]
	v_pk_mul_f32 v[126:127], v[126:127], v[206:207] op_sel_hi:[1,0]
	v_pk_mul_f32 v[124:125], v[124:125], v[144:145]
	v_pk_mul_f32 v[126:127], v[126:127], v[146:147]
	v_pk_mul_f32 v[116:117], v[116:117], v[206:207] op_sel_hi:[1,0]
	v_pk_mul_f32 v[118:119], v[118:119], v[206:207] op_sel_hi:[1,0]
	v_pk_mul_f32 v[116:117], v[116:117], v[148:149]
	v_pk_mul_f32 v[118:119], v[118:119], v[150:151]
	v_pk_mul_f32 v[100:101], v[100:101], v[206:207] op_sel_hi:[1,0]
	v_pk_mul_f32 v[102:103], v[102:103], v[206:207] op_sel_hi:[1,0]
	v_pk_mul_f32 v[100:101], v[100:101], v[152:153]
	v_pk_mul_f32 v[102:103], v[102:103], v[154:155]
	v_pk_mul_f32 v[96:97], v[96:97], v[206:207] op_sel_hi:[1,0]
	v_pk_mul_f32 v[98:99], v[98:99], v[206:207] op_sel_hi:[1,0]
	v_pk_mul_f32 v[96:97], v[96:97], v[156:157]
	v_pk_mul_f32 v[98:99], v[98:99], v[158:159]
	global_store_dwordx4 v173, v[124:127], s[86:87]
	global_store_dwordx4 v173, v[116:119], s[86:87] offset:64
	global_store_dwordx4 v173, v[100:103], s[86:87] offset:512
	global_store_dwordx4 v173, v[96:99], s[86:87] offset:576
	s_add_u32 s86, s82, 0x40000
	s_addc_u32 s87, s83, 0
	v_pk_mul_f32 v[92:93], v[92:93], v[208:209] op_sel_hi:[1,0]
	v_pk_mul_f32 v[94:95], v[94:95], v[208:209] op_sel_hi:[1,0]
	v_pk_mul_f32 v[92:93], v[92:93], v[144:145]
	v_pk_mul_f32 v[94:95], v[94:95], v[146:147]
	v_pk_mul_f32 v[88:89], v[88:89], v[208:209] op_sel_hi:[1,0]
	v_pk_mul_f32 v[90:91], v[90:91], v[208:209] op_sel_hi:[1,0]
	v_pk_mul_f32 v[88:89], v[88:89], v[148:149]
	v_pk_mul_f32 v[90:91], v[90:91], v[150:151]
	v_pk_mul_f32 v[84:85], v[84:85], v[208:209] op_sel_hi:[1,0]
	v_pk_mul_f32 v[86:87], v[86:87], v[208:209] op_sel_hi:[1,0]
	v_pk_mul_f32 v[84:85], v[84:85], v[152:153]
	v_pk_mul_f32 v[86:87], v[86:87], v[154:155]
	v_pk_mul_f32 v[80:81], v[80:81], v[208:209] op_sel_hi:[1,0]
	v_pk_mul_f32 v[82:83], v[82:83], v[208:209] op_sel_hi:[1,0]
	v_pk_mul_f32 v[80:81], v[80:81], v[156:157]
	v_pk_mul_f32 v[82:83], v[82:83], v[158:159]
	global_store_dwordx4 v173, v[92:95], s[86:87]
	global_store_dwordx4 v173, v[88:91], s[86:87] offset:64
	global_store_dwordx4 v173, v[84:87], s[86:87] offset:512
	global_store_dwordx4 v173, v[80:83], s[86:87] offset:576
	s_add_u32 s86, s82, 0x60000
	s_addc_u32 s87, s83, 0
	v_pk_mul_f32 v[76:77], v[76:77], v[210:211] op_sel_hi:[1,0]
	v_pk_mul_f32 v[78:79], v[78:79], v[210:211] op_sel_hi:[1,0]
	v_pk_mul_f32 v[76:77], v[76:77], v[144:145]
	v_pk_mul_f32 v[78:79], v[78:79], v[146:147]
	v_pk_mul_f32 v[72:73], v[72:73], v[210:211] op_sel_hi:[1,0]
	v_pk_mul_f32 v[74:75], v[74:75], v[210:211] op_sel_hi:[1,0]
	v_pk_mul_f32 v[72:73], v[72:73], v[148:149]
	v_pk_mul_f32 v[74:75], v[74:75], v[150:151]
	v_pk_mul_f32 v[68:69], v[68:69], v[210:211] op_sel_hi:[1,0]
	v_pk_mul_f32 v[70:71], v[70:71], v[210:211] op_sel_hi:[1,0]
	v_pk_mul_f32 v[68:69], v[68:69], v[152:153]
	v_pk_mul_f32 v[70:71], v[70:71], v[154:155]
	v_pk_mul_f32 v[64:65], v[64:65], v[210:211] op_sel_hi:[1,0]
	v_pk_mul_f32 v[66:67], v[66:67], v[210:211] op_sel_hi:[1,0]
	v_pk_mul_f32 v[64:65], v[64:65], v[156:157]
	v_pk_mul_f32 v[66:67], v[66:67], v[158:159]
	global_store_dwordx4 v173, v[76:79], s[86:87]
	global_store_dwordx4 v173, v[72:75], s[86:87] offset:64
	global_store_dwordx4 v173, v[68:71], s[86:87] offset:512
	global_store_dwordx4 v173, v[64:67], s[86:87] offset:576
	s_waitcnt vmcnt(16)
	s_branch .Lepi_e2
